# K loops (FFN-up/down, W_out, W_in): seg-1 LDS fragment reads issued before the scalar pointer arithmetic, loop-tail increments moved in front of the last barrier, one spurious mid-burst lgkmcnt(0) rem
# baseline (speedup 1.0000x reference)
.LBB0_122:
	s_add_i32 s35, 0, 0x10000
	v_add_u32_e32 v140, s35, v142
	s_add_i32 s49, 0, 0x14000
	ds_read_b128 v[136:139], v140
	ds_read_b128 v[144:147], v140 offset:1024
	ds_read_b128 v[148:151], v140 offset:2048
	ds_read_b128 v[152:155], v140 offset:3072
	v_add_u32_e32 v140, s49, v142
	ds_read_b128 v[156:159], v140
	ds_read_b128 v[160:163], v140 offset:1024
	ds_read_b128 v[164:167], v140 offset:2048
	ds_read_b128 v[168:171], v140 offset:3072
	ds_read_b128 v[172:175], v143
	ds_read_b128 v[176:179], v143 offset:1024
	ds_read_b128 v[180:183], v143 offset:2048
	ds_read_b128 v[184:187], v143 offset:3072
	ds_read_b128 v[188:191], v143 offset:4096
	ds_read_b128 v[192:195], v143 offset:5120
	ds_read_b128 v[196:199], v143 offset:6144
	ds_read_b128 v[200:203], v143 offset:7168
	s_cmp_eq_u32 s89, 12
	s_cselect_b32 s42, s20, s65
	s_cselect_b32 s43, s16, s86
	s_cselect_b32 s45, s31, s88
	s_cselect_b32 s44, s59, s87
	s_add_u32 s38, s42, 0x80
	s_addc_u32 s39, s43, 0
	s_add_u32 s74, s44, 0x80
	s_addc_u32 s75, s45, 0
	s_mov_b64 s[18:19], s[68:69]
	s_mov_b32 m0, s81
	s_nop 0
	global_load_lds_dwordx4 v130, s[18:19]
	s_mov_b32 m0, s82
	s_nop 0
	global_load_lds_dwordx4 v132, s[18:19]
	s_add_u32 s18, s18, 0x40000
	s_addc_u32 s19, s19, 0
	s_add_i32 m0, s67, 0xc000
	s_nop 0
	global_load_lds_dwordx4 v130, s[18:19]
	s_add_i32 m0, s67, 0xe000
	s_nop 0
	global_load_lds_dwordx4 v132, s[18:19]
	s_waitcnt vmcnt(8)
	s_waitcnt lgkmcnt(0)
	s_barrier
	s_setprio 1
	s_waitcnt lgkmcnt(0)
	v_mfma_f32_16x16x32_bf16 v[126:129], v[136:139], v[172:175], v[126:129]
	v_mfma_f32_16x16x32_bf16 v[122:125], v[148:151], v[172:175], v[122:125]
	v_mfma_f32_16x16x32_bf16 v[110:113], v[136:139], v[180:183], v[110:113]
	v_mfma_f32_16x16x32_bf16 v[106:109], v[148:151], v[180:183], v[106:109]
	v_mfma_f32_16x16x32_bf16 v[92:95], v[136:139], v[188:191], v[92:95]
	v_mfma_f32_16x16x32_bf16 v[88:91], v[148:151], v[188:191], v[88:91]
	v_mfma_f32_16x16x32_bf16 v[76:79], v[136:139], v[196:199], v[76:79]
	v_mfma_f32_16x16x32_bf16 v[72:75], v[148:151], v[196:199], v[72:75]
	v_mfma_f32_16x16x32_bf16 v[126:129], v[144:147], v[176:179], v[126:129]
	v_mfma_f32_16x16x32_bf16 v[122:125], v[152:155], v[176:179], v[122:125]
	v_mfma_f32_16x16x32_bf16 v[110:113], v[144:147], v[184:187], v[110:113]
	v_mfma_f32_16x16x32_bf16 v[106:109], v[152:155], v[184:187], v[106:109]
	v_mfma_f32_16x16x32_bf16 v[92:95], v[144:147], v[192:195], v[92:95]
	v_mfma_f32_16x16x32_bf16 v[88:91], v[152:155], v[192:195], v[88:91]
	v_mfma_f32_16x16x32_bf16 v[76:79], v[144:147], v[200:203], v[76:79]
	v_mfma_f32_16x16x32_bf16 v[72:75], v[152:155], v[200:203], v[72:75]
	v_mfma_f32_16x16x32_bf16 v[118:121], v[156:159], v[172:175], v[118:121]
	v_mfma_f32_16x16x32_bf16 v[114:117], v[164:167], v[172:175], v[114:117]
	v_mfma_f32_16x16x32_bf16 v[102:105], v[156:159], v[180:183], v[102:105]
	v_mfma_f32_16x16x32_bf16 v[98:101], v[164:167], v[180:183], v[98:101]
	v_mfma_f32_16x16x32_bf16 v[84:87], v[156:159], v[188:191], v[84:87]
	v_mfma_f32_16x16x32_bf16 v[80:83], v[164:167], v[188:191], v[80:83]
	v_mfma_f32_16x16x32_bf16 v[68:71], v[156:159], v[196:199], v[68:71]
	v_mfma_f32_16x16x32_bf16 v[64:67], v[164:167], v[196:199], v[64:67]
	v_mfma_f32_16x16x32_bf16 v[118:121], v[160:163], v[176:179], v[118:121]
	v_mfma_f32_16x16x32_bf16 v[114:117], v[168:171], v[176:179], v[114:117]
	v_mfma_f32_16x16x32_bf16 v[102:105], v[160:163], v[184:187], v[102:105]
	v_mfma_f32_16x16x32_bf16 v[98:101], v[168:171], v[184:187], v[98:101]
	v_mfma_f32_16x16x32_bf16 v[84:87], v[160:163], v[192:195], v[84:87]
	v_mfma_f32_16x16x32_bf16 v[80:83], v[168:171], v[192:195], v[80:83]
	v_mfma_f32_16x16x32_bf16 v[68:71], v[160:163], v[200:203], v[68:71]
	v_mfma_f32_16x16x32_bf16 v[64:67], v[168:171], v[200:203], v[64:67]
	s_setprio 0
	s_barrier
	s_add_i32 s18, s35, s14
	s_mov_b32 m0, s18
	ds_read_b128 v[172:175], v143 offset:16384
	ds_read_b128 v[176:179], v143 offset:17408
	ds_read_b128 v[180:183], v143 offset:18432
	ds_read_b128 v[184:187], v143 offset:19456
	ds_read_b128 v[188:191], v143 offset:20480
	ds_read_b128 v[192:195], v143 offset:21504
	ds_read_b128 v[196:199], v143 offset:22528
	ds_read_b128 v[200:203], v143 offset:23552
	global_load_lds_dwordx4 v96, s[44:45]
	s_add_i32 m0, s18, 0x2000
	s_add_u32 s18, s44, 0x40000
	s_addc_u32 s19, s45, 0
	s_add_i32 s35, s49, s14
	global_load_lds_dwordx4 v134, s[44:45]
	s_mov_b32 m0, s35
	s_nop 0
	global_load_lds_dwordx4 v96, s[18:19]
	s_add_i32 m0, s35, 0x2000
	s_nop 0
	global_load_lds_dwordx4 v134, s[18:19]
	s_waitcnt vmcnt(6)
	s_waitcnt lgkmcnt(0)
	s_barrier
	s_setprio 1
	s_waitcnt lgkmcnt(0)
	v_mfma_f32_16x16x32_bf16 v[60:63], v[136:139], v[172:175], v[60:63]
	v_mfma_f32_16x16x32_bf16 v[56:59], v[148:151], v[172:175], v[56:59]
	v_mfma_f32_16x16x32_bf16 v[44:47], v[136:139], v[180:183], v[44:47]
	v_mfma_f32_16x16x32_bf16 v[40:43], v[148:151], v[180:183], v[40:43]
	v_mfma_f32_16x16x32_bf16 v[28:31], v[136:139], v[188:191], v[28:31]
	v_mfma_f32_16x16x32_bf16 v[24:27], v[148:151], v[188:191], v[24:27]
	v_mfma_f32_16x16x32_bf16 v[12:15], v[136:139], v[196:199], v[12:15]
	v_mfma_f32_16x16x32_bf16 v[8:11], v[148:151], v[196:199], v[8:11]
	v_mfma_f32_16x16x32_bf16 v[60:63], v[144:147], v[176:179], v[60:63]
	v_mfma_f32_16x16x32_bf16 v[56:59], v[152:155], v[176:179], v[56:59]
	v_mfma_f32_16x16x32_bf16 v[44:47], v[144:147], v[184:187], v[44:47]
	v_mfma_f32_16x16x32_bf16 v[40:43], v[152:155], v[184:187], v[40:43]
	v_mfma_f32_16x16x32_bf16 v[28:31], v[144:147], v[192:195], v[28:31]
	v_mfma_f32_16x16x32_bf16 v[24:27], v[152:155], v[192:195], v[24:27]
	v_mfma_f32_16x16x32_bf16 v[12:15], v[144:147], v[200:203], v[12:15]
	v_mfma_f32_16x16x32_bf16 v[8:11], v[152:155], v[200:203], v[8:11]
	v_mfma_f32_16x16x32_bf16 v[52:55], v[156:159], v[172:175], v[52:55]
	v_mfma_f32_16x16x32_bf16 v[48:51], v[164:167], v[172:175], v[48:51]
	v_mfma_f32_16x16x32_bf16 v[36:39], v[156:159], v[180:183], v[36:39]
	v_mfma_f32_16x16x32_bf16 v[32:35], v[164:167], v[180:183], v[32:35]
	v_mfma_f32_16x16x32_bf16 v[20:23], v[156:159], v[188:191], v[20:23]
	v_mfma_f32_16x16x32_bf16 v[16:19], v[164:167], v[188:191], v[16:19]
	v_mfma_f32_16x16x32_bf16 v[4:7], v[156:159], v[196:199], v[4:7]
	v_mfma_f32_16x16x32_bf16 v[0:3], v[164:167], v[196:199], v[0:3]
	v_mfma_f32_16x16x32_bf16 v[52:55], v[160:163], v[176:179], v[52:55]
	v_mfma_f32_16x16x32_bf16 v[48:51], v[168:171], v[176:179], v[48:51]
	v_mfma_f32_16x16x32_bf16 v[36:39], v[160:163], v[184:187], v[36:39]
	v_mfma_f32_16x16x32_bf16 v[32:35], v[168:171], v[184:187], v[32:35]
	v_mfma_f32_16x16x32_bf16 v[20:23], v[160:163], v[192:195], v[20:23]
	v_mfma_f32_16x16x32_bf16 v[16:19], v[168:171], v[192:195], v[16:19]
	v_mfma_f32_16x16x32_bf16 v[4:7], v[160:163], v[200:203], v[4:7]
	v_mfma_f32_16x16x32_bf16 v[0:3], v[168:171], v[200:203], v[0:3]
	s_setprio 0
	s_barrier
	s_add_i32 s35, 0, 0x18000
	v_add_u32_e32 v140, s35, v142
	s_add_i32 s44, 0, 0x1c000
	ds_read_b128 v[136:139], v140
	ds_read_b128 v[144:147], v140 offset:1024
	ds_read_b128 v[148:151], v140 offset:2048
	ds_read_b128 v[152:155], v140 offset:3072
	v_add_u32_e32 v140, s44, v142
	ds_read_b128 v[156:159], v140
	ds_read_b128 v[160:163], v140 offset:1024
	ds_read_b128 v[164:167], v140 offset:2048
	ds_read_b128 v[168:171], v140 offset:3072
	s_mov_b32 m0, s67
	s_nop 0
	global_load_lds_dwordx4 v130, s[42:43]
	s_mov_b32 m0, s73
	s_nop 0
	global_load_lds_dwordx4 v132, s[42:43]
	s_add_u32 s18, s42, 0x40000
	s_addc_u32 s19, s43, 0
	s_mov_b32 m0, s76
	ds_read_b128 v[172:175], v143 offset:32768
	ds_read_b128 v[176:179], v143 offset:33792
	ds_read_b128 v[180:183], v143 offset:34816
	ds_read_b128 v[184:187], v143 offset:35840
	ds_read_b128 v[188:191], v143 offset:36864
	ds_read_b128 v[192:195], v143 offset:37888
	ds_read_b128 v[196:199], v143 offset:38912
	ds_read_b128 v[200:203], v143 offset:39936
	global_load_lds_dwordx4 v130, s[18:19]
	s_mov_b32 m0, s77
	s_nop 0
	global_load_lds_dwordx4 v132, s[18:19]
	s_waitcnt vmcnt(8)
	s_waitcnt lgkmcnt(0)
	s_barrier
	s_setprio 1
	s_waitcnt lgkmcnt(0)
	v_mfma_f32_16x16x32_bf16 v[126:129], v[136:139], v[172:175], v[126:129]
	v_mfma_f32_16x16x32_bf16 v[122:125], v[148:151], v[172:175], v[122:125]
	v_mfma_f32_16x16x32_bf16 v[110:113], v[136:139], v[180:183], v[110:113]
	v_mfma_f32_16x16x32_bf16 v[106:109], v[148:151], v[180:183], v[106:109]
	v_mfma_f32_16x16x32_bf16 v[92:95], v[136:139], v[188:191], v[92:95]
	v_mfma_f32_16x16x32_bf16 v[88:91], v[148:151], v[188:191], v[88:91]
	v_mfma_f32_16x16x32_bf16 v[76:79], v[136:139], v[196:199], v[76:79]
	v_mfma_f32_16x16x32_bf16 v[72:75], v[148:151], v[196:199], v[72:75]
	v_mfma_f32_16x16x32_bf16 v[126:129], v[144:147], v[176:179], v[126:129]
	v_mfma_f32_16x16x32_bf16 v[122:125], v[152:155], v[176:179], v[122:125]
	v_mfma_f32_16x16x32_bf16 v[110:113], v[144:147], v[184:187], v[110:113]
	v_mfma_f32_16x16x32_bf16 v[106:109], v[152:155], v[184:187], v[106:109]
	v_mfma_f32_16x16x32_bf16 v[92:95], v[144:147], v[192:195], v[92:95]
	v_mfma_f32_16x16x32_bf16 v[88:91], v[152:155], v[192:195], v[88:91]
	v_mfma_f32_16x16x32_bf16 v[76:79], v[144:147], v[200:203], v[76:79]
	v_mfma_f32_16x16x32_bf16 v[72:75], v[152:155], v[200:203], v[72:75]
	v_mfma_f32_16x16x32_bf16 v[118:121], v[156:159], v[172:175], v[118:121]
	v_mfma_f32_16x16x32_bf16 v[114:117], v[164:167], v[172:175], v[114:117]
	v_mfma_f32_16x16x32_bf16 v[102:105], v[156:159], v[180:183], v[102:105]
	v_mfma_f32_16x16x32_bf16 v[98:101], v[164:167], v[180:183], v[98:101]
	v_mfma_f32_16x16x32_bf16 v[84:87], v[156:159], v[188:191], v[84:87]
	v_mfma_f32_16x16x32_bf16 v[80:83], v[164:167], v[188:191], v[80:83]
	v_mfma_f32_16x16x32_bf16 v[68:71], v[156:159], v[196:199], v[68:71]
	v_mfma_f32_16x16x32_bf16 v[64:67], v[164:167], v[196:199], v[64:67]
	v_mfma_f32_16x16x32_bf16 v[118:121], v[160:163], v[176:179], v[118:121]
	v_mfma_f32_16x16x32_bf16 v[114:117], v[168:171], v[176:179], v[114:117]
	v_mfma_f32_16x16x32_bf16 v[102:105], v[160:163], v[184:187], v[102:105]
	v_mfma_f32_16x16x32_bf16 v[98:101], v[168:171], v[184:187], v[98:101]
	v_mfma_f32_16x16x32_bf16 v[84:87], v[160:163], v[192:195], v[84:87]
	v_mfma_f32_16x16x32_bf16 v[80:83], v[168:171], v[192:195], v[80:83]
	v_mfma_f32_16x16x32_bf16 v[68:71], v[160:163], v[200:203], v[68:71]
	v_mfma_f32_16x16x32_bf16 v[64:67], v[168:171], v[200:203], v[64:67]
	s_setprio 0
	s_barrier
	s_add_i32 s18, s35, s14
	s_mov_b32 m0, s18
	ds_read_b128 v[172:175], v143 offset:49152
	ds_read_b128 v[176:179], v143 offset:50176
	ds_read_b128 v[180:183], v143 offset:51200
	ds_read_b128 v[184:187], v143 offset:52224
	ds_read_b128 v[188:191], v143 offset:53248
	ds_read_b128 v[192:195], v143 offset:54272
	ds_read_b128 v[196:199], v143 offset:55296
	ds_read_b128 v[200:203], v143 offset:56320
	global_load_lds_dwordx4 v96, s[74:75]
	s_add_i32 m0, s18, 0x2000
	s_add_u32 s18, s74, 0x40000
	s_addc_u32 s19, s75, 0
	s_add_i32 s35, s44, s14
	global_load_lds_dwordx4 v134, s[74:75]
	s_mov_b32 m0, s35
	s_nop 0
	global_load_lds_dwordx4 v96, s[18:19]
	s_add_i32 m0, s35, 0x2000
	s_nop 0
	global_load_lds_dwordx4 v134, s[18:19]
	s_waitcnt vmcnt(6)
	s_waitcnt lgkmcnt(0)
	s_barrier
	s_setprio 1
	s_waitcnt lgkmcnt(0)
	v_mfma_f32_16x16x32_bf16 v[60:63], v[136:139], v[172:175], v[60:63]
	v_mfma_f32_16x16x32_bf16 v[56:59], v[148:151], v[172:175], v[56:59]
	v_mfma_f32_16x16x32_bf16 v[44:47], v[136:139], v[180:183], v[44:47]
	v_mfma_f32_16x16x32_bf16 v[40:43], v[148:151], v[180:183], v[40:43]
	v_mfma_f32_16x16x32_bf16 v[28:31], v[136:139], v[188:191], v[28:31]
	v_mfma_f32_16x16x32_bf16 v[24:27], v[148:151], v[188:191], v[24:27]
	v_mfma_f32_16x16x32_bf16 v[12:15], v[136:139], v[196:199], v[12:15]
	v_mfma_f32_16x16x32_bf16 v[8:11], v[148:151], v[196:199], v[8:11]
	v_mfma_f32_16x16x32_bf16 v[60:63], v[144:147], v[176:179], v[60:63]
	v_mfma_f32_16x16x32_bf16 v[56:59], v[152:155], v[176:179], v[56:59]
	v_mfma_f32_16x16x32_bf16 v[44:47], v[144:147], v[184:187], v[44:47]
	v_mfma_f32_16x16x32_bf16 v[40:43], v[152:155], v[184:187], v[40:43]
	v_mfma_f32_16x16x32_bf16 v[28:31], v[144:147], v[192:195], v[28:31]
	v_mfma_f32_16x16x32_bf16 v[24:27], v[152:155], v[192:195], v[24:27]
	v_mfma_f32_16x16x32_bf16 v[12:15], v[144:147], v[200:203], v[12:15]
	v_mfma_f32_16x16x32_bf16 v[8:11], v[152:155], v[200:203], v[8:11]
	v_mfma_f32_16x16x32_bf16 v[52:55], v[156:159], v[172:175], v[52:55]
	v_mfma_f32_16x16x32_bf16 v[48:51], v[164:167], v[172:175], v[48:51]
	v_mfma_f32_16x16x32_bf16 v[36:39], v[156:159], v[180:183], v[36:39]
	v_mfma_f32_16x16x32_bf16 v[32:35], v[164:167], v[180:183], v[32:35]
	v_mfma_f32_16x16x32_bf16 v[20:23], v[156:159], v[188:191], v[20:23]
	v_mfma_f32_16x16x32_bf16 v[16:19], v[164:167], v[188:191], v[16:19]
	v_mfma_f32_16x16x32_bf16 v[4:7], v[156:159], v[196:199], v[4:7]
	v_mfma_f32_16x16x32_bf16 v[0:3], v[164:167], v[196:199], v[0:3]
	v_mfma_f32_16x16x32_bf16 v[52:55], v[160:163], v[176:179], v[52:55]
	v_mfma_f32_16x16x32_bf16 v[48:51], v[168:171], v[176:179], v[48:51]
	v_mfma_f32_16x16x32_bf16 v[36:39], v[160:163], v[184:187], v[36:39]
	v_mfma_f32_16x16x32_bf16 v[32:35], v[168:171], v[184:187], v[32:35]
	v_mfma_f32_16x16x32_bf16 v[20:23], v[160:163], v[192:195], v[20:23]
	v_mfma_f32_16x16x32_bf16 v[16:19], v[168:171], v[192:195], v[16:19]
	v_mfma_f32_16x16x32_bf16 v[4:7], v[160:163], v[200:203], v[4:7]
	v_mfma_f32_16x16x32_bf16 v[0:3], v[168:171], v[200:203], v[0:3]
	s_add_i32 s89, s89, 2
	s_add_u32 s65, s65, 0x100
	s_addc_u32 s86, s86, 0
	s_add_u32 s87, s87, 0x100
	s_addc_u32 s88, s88, 0
	s_add_u32 s68, s68, 0x100
	s_addc_u32 s69, s69, 0
	s_setprio 0
	s_barrier
	s_cmp_gt_u32 s89, 13
	s_cbranch_scc0 .LBB0_122
	s_and_b64 vcc, exec, s[28:29]
	s_cbranch_vccz .LBB0_125
	s_barrier

.LBB0_433:
	s_add_i32 s35, 0, 0x10000
	s_add_i32 s49, 0, 0x14000
	v_add_u32_e32 v96, s35, v199
	v_add_u32_e32 v166, s49, v199
	ds_read_b128 v[138:141], v96
	ds_read_b128 v[142:145], v96 offset:1024
	ds_read_b128 v[146:149], v96 offset:2048
	ds_read_b128 v[150:153], v96 offset:3072
	ds_read_b128 v[154:157], v166
	ds_read_b128 v[158:161], v166 offset:1024
	ds_read_b128 v[162:165], v166 offset:2048
	ds_read_b128 v[166:169], v166 offset:3072
	ds_read_b128 v[170:173], v200
	ds_read_b128 v[174:177], v200 offset:1024
	ds_read_b128 v[178:181], v200 offset:2048
	ds_read_b128 v[182:185], v200 offset:3072
	ds_read_b128 v[190:193], v200 offset:4096
	ds_read_b128 v[194:197], v200 offset:5120
	ds_read_b128 v[202:205], v200 offset:6144
	ds_read_b128 v[206:209], v200 offset:7168
	s_add_u32 s18, s10, 0x80
	s_addc_u32 s19, s11, 0
	s_add_u32 s10, s10, 0x100
	s_addc_u32 s11, s11, 0
	s_cmp_eq_u32 s92, 12
	s_cselect_b32 s42, s87, s10
	s_cselect_b32 s43, s9, s11
	s_cselect_b32 s45, s85, s94
	s_cselect_b32 s44, vcc_lo, vcc_hi
	s_add_u32 s38, s42, 0x80
	s_addc_u32 s39, s43, 0
	s_add_u32 s68, s44, 0x80
	s_addc_u32 s69, s45, 0
	s_mov_b32 m0, s29
	s_nop 0
	global_load_lds_dwordx4 v130, s[18:19]
	s_mov_b32 m0, s16
	s_nop 0
	global_load_lds_dwordx4 v134, s[18:19]
	s_add_u32 s18, s18, 0x40000
	s_addc_u32 s19, s19, 0
	s_add_i32 m0, s73, 0xc000
	s_nop 0
	global_load_lds_dwordx4 v130, s[18:19]
	s_add_i32 m0, s73, 0xe000
	s_nop 0
	global_load_lds_dwordx4 v134, s[18:19]
	s_waitcnt vmcnt(8)
	s_waitcnt lgkmcnt(0)
	s_barrier
	s_setprio 1
	s_waitcnt lgkmcnt(0)
	v_mfma_f32_16x16x32_bf16 v[126:129], v[138:141], v[170:173], v[126:129]
	v_mfma_f32_16x16x32_bf16 v[122:125], v[146:149], v[170:173], v[122:125]
	v_mfma_f32_16x16x32_bf16 v[118:121], v[138:141], v[178:181], v[118:121]
	v_mfma_f32_16x16x32_bf16 v[110:113], v[146:149], v[178:181], v[110:113]
	v_mfma_f32_16x16x32_bf16 v[102:105], v[138:141], v[190:193], v[102:105]
	v_mfma_f32_16x16x32_bf16 v[92:95], v[146:149], v[190:193], v[92:95]
	v_mfma_f32_16x16x32_bf16 v[84:87], v[138:141], v[202:205], v[84:87]
	v_mfma_f32_16x16x32_bf16 v[76:79], v[146:149], v[202:205], v[76:79]
	v_mfma_f32_16x16x32_bf16 v[126:129], v[142:145], v[174:177], v[126:129]
	v_mfma_f32_16x16x32_bf16 v[122:125], v[150:153], v[174:177], v[122:125]
	v_mfma_f32_16x16x32_bf16 v[118:121], v[142:145], v[182:185], v[118:121]
	v_mfma_f32_16x16x32_bf16 v[110:113], v[150:153], v[182:185], v[110:113]
	v_mfma_f32_16x16x32_bf16 v[102:105], v[142:145], v[194:197], v[102:105]
	v_mfma_f32_16x16x32_bf16 v[92:95], v[150:153], v[194:197], v[92:95]
	v_mfma_f32_16x16x32_bf16 v[84:87], v[142:145], v[206:209], v[84:87]
	v_mfma_f32_16x16x32_bf16 v[76:79], v[150:153], v[206:209], v[76:79]
	v_mfma_f32_16x16x32_bf16 v[114:117], v[154:157], v[170:173], v[114:117]
	v_mfma_f32_16x16x32_bf16 v[106:109], v[162:165], v[170:173], v[106:109]
	v_mfma_f32_16x16x32_bf16 v[98:101], v[154:157], v[178:181], v[98:101]
	v_mfma_f32_16x16x32_bf16 v[88:91], v[162:165], v[178:181], v[88:91]
	v_mfma_f32_16x16x32_bf16 v[80:83], v[154:157], v[190:193], v[80:83]
	v_mfma_f32_16x16x32_bf16 v[72:75], v[162:165], v[190:193], v[72:75]
	v_mfma_f32_16x16x32_bf16 v[68:71], v[154:157], v[202:205], v[68:71]
	v_mfma_f32_16x16x32_bf16 v[64:67], v[162:165], v[202:205], v[64:67]
	v_mfma_f32_16x16x32_bf16 v[114:117], v[158:161], v[174:177], v[114:117]
	v_mfma_f32_16x16x32_bf16 v[106:109], v[166:169], v[174:177], v[106:109]
	v_mfma_f32_16x16x32_bf16 v[98:101], v[158:161], v[182:185], v[98:101]
	v_mfma_f32_16x16x32_bf16 v[88:91], v[166:169], v[182:185], v[88:91]
	v_mfma_f32_16x16x32_bf16 v[80:83], v[158:161], v[194:197], v[80:83]
	v_mfma_f32_16x16x32_bf16 v[72:75], v[166:169], v[194:197], v[72:75]
	v_mfma_f32_16x16x32_bf16 v[68:71], v[158:161], v[206:209], v[68:71]
	v_mfma_f32_16x16x32_bf16 v[64:67], v[166:169], v[206:209], v[64:67]
	s_setprio 0
	s_barrier
	s_add_i32 s18, s35, s72
	s_mov_b32 m0, s18
	ds_read_b128 v[170:173], v200 offset:16384
	ds_read_b128 v[174:177], v200 offset:17408
	ds_read_b128 v[178:181], v200 offset:18432
	ds_read_b128 v[182:185], v200 offset:19456
	ds_read_b128 v[190:193], v200 offset:20480
	ds_read_b128 v[194:197], v200 offset:21504
	ds_read_b128 v[202:205], v200 offset:22528
	ds_read_b128 v[206:209], v200 offset:23552
	global_load_lds_dwordx4 v132, s[44:45]
	s_add_i32 m0, s18, 0x2000
	s_add_u32 s18, s44, 0x40000
	s_addc_u32 s19, s45, 0
	s_add_i32 s35, s49, s72
	global_load_lds_dwordx4 v136, s[44:45]
	s_mov_b32 m0, s35
	s_nop 0
	global_load_lds_dwordx4 v132, s[18:19]
	s_add_i32 m0, s35, 0x2000
	s_nop 0
	global_load_lds_dwordx4 v136, s[18:19]
	s_waitcnt vmcnt(6)
	s_waitcnt lgkmcnt(0)
	s_barrier
	s_setprio 1
	s_waitcnt lgkmcnt(0)
	v_mfma_f32_16x16x32_bf16 v[60:63], v[138:141], v[170:173], v[60:63]
	v_mfma_f32_16x16x32_bf16 v[56:59], v[146:149], v[170:173], v[56:59]
	v_mfma_f32_16x16x32_bf16 v[52:55], v[138:141], v[178:181], v[52:55]
	v_mfma_f32_16x16x32_bf16 v[44:47], v[146:149], v[178:181], v[44:47]
	v_mfma_f32_16x16x32_bf16 v[36:39], v[138:141], v[190:193], v[36:39]
	v_mfma_f32_16x16x32_bf16 v[28:31], v[146:149], v[190:193], v[28:31]
	v_mfma_f32_16x16x32_bf16 v[20:23], v[138:141], v[202:205], v[20:23]
	v_mfma_f32_16x16x32_bf16 v[12:15], v[146:149], v[202:205], v[12:15]
	v_mfma_f32_16x16x32_bf16 v[60:63], v[142:145], v[174:177], v[60:63]
	v_mfma_f32_16x16x32_bf16 v[56:59], v[150:153], v[174:177], v[56:59]
	v_mfma_f32_16x16x32_bf16 v[52:55], v[142:145], v[182:185], v[52:55]
	v_mfma_f32_16x16x32_bf16 v[44:47], v[150:153], v[182:185], v[44:47]
	v_mfma_f32_16x16x32_bf16 v[36:39], v[142:145], v[194:197], v[36:39]
	v_mfma_f32_16x16x32_bf16 v[28:31], v[150:153], v[194:197], v[28:31]
	v_mfma_f32_16x16x32_bf16 v[20:23], v[142:145], v[206:209], v[20:23]
	v_mfma_f32_16x16x32_bf16 v[12:15], v[150:153], v[206:209], v[12:15]
	v_mfma_f32_16x16x32_bf16 v[48:51], v[154:157], v[170:173], v[48:51]
	v_mfma_f32_16x16x32_bf16 v[40:43], v[162:165], v[170:173], v[40:43]
	v_mfma_f32_16x16x32_bf16 v[32:35], v[154:157], v[178:181], v[32:35]
	v_mfma_f32_16x16x32_bf16 v[24:27], v[162:165], v[178:181], v[24:27]
	v_mfma_f32_16x16x32_bf16 v[16:19], v[154:157], v[190:193], v[16:19]
	v_mfma_f32_16x16x32_bf16 v[8:11], v[162:165], v[190:193], v[8:11]
	v_mfma_f32_16x16x32_bf16 v[4:7], v[154:157], v[202:205], v[4:7]
	v_mfma_f32_16x16x32_bf16 v[0:3], v[162:165], v[202:205], v[0:3]
	v_mfma_f32_16x16x32_bf16 v[48:51], v[158:161], v[174:177], v[48:51]
	v_mfma_f32_16x16x32_bf16 v[40:43], v[166:169], v[174:177], v[40:43]
	v_mfma_f32_16x16x32_bf16 v[32:35], v[158:161], v[182:185], v[32:35]
	v_mfma_f32_16x16x32_bf16 v[24:27], v[166:169], v[182:185], v[24:27]
	v_mfma_f32_16x16x32_bf16 v[16:19], v[158:161], v[194:197], v[16:19]
	v_mfma_f32_16x16x32_bf16 v[8:11], v[166:169], v[194:197], v[8:11]
	v_mfma_f32_16x16x32_bf16 v[4:7], v[158:161], v[206:209], v[4:7]
	v_mfma_f32_16x16x32_bf16 v[0:3], v[166:169], v[206:209], v[0:3]
	s_setprio 0
	s_barrier
	s_add_i32 s35, 0, 0x18000
	v_add_u32_e32 v96, s35, v199
	s_add_i32 s44, 0, 0x1c000
	ds_read_b128 v[138:141], v96
	ds_read_b128 v[142:145], v96 offset:1024
	ds_read_b128 v[146:149], v96 offset:2048
	ds_read_b128 v[150:153], v96 offset:3072
	v_add_u32_e32 v96, s44, v199
	ds_read_b128 v[154:157], v96
	ds_read_b128 v[158:161], v96 offset:1024
	ds_read_b128 v[162:165], v96 offset:2048
	ds_read_b128 v[166:169], v96 offset:3072
	s_mov_b32 m0, s73
	s_nop 0
	global_load_lds_dwordx4 v130, s[42:43]
	s_mov_b32 m0, s74
	s_nop 0
	global_load_lds_dwordx4 v134, s[42:43]
	s_add_u32 s18, s42, 0x40000
	s_addc_u32 s19, s43, 0
	s_mov_b32 m0, s75
	ds_read_b128 v[170:173], v200 offset:32768
	ds_read_b128 v[174:177], v200 offset:33792
	ds_read_b128 v[178:181], v200 offset:34816
	ds_read_b128 v[182:185], v200 offset:35840
	ds_read_b128 v[190:193], v200 offset:36864
	ds_read_b128 v[194:197], v200 offset:37888
	ds_read_b128 v[202:205], v200 offset:38912
	ds_read_b128 v[206:209], v200 offset:39936
	global_load_lds_dwordx4 v130, s[18:19]
	s_mov_b32 m0, s83
	s_nop 0
	global_load_lds_dwordx4 v134, s[18:19]
	s_waitcnt vmcnt(8)
	s_waitcnt lgkmcnt(0)
	s_barrier
	s_setprio 1
	s_waitcnt lgkmcnt(0)
	v_mfma_f32_16x16x32_bf16 v[126:129], v[138:141], v[170:173], v[126:129]
	v_mfma_f32_16x16x32_bf16 v[122:125], v[146:149], v[170:173], v[122:125]
	v_mfma_f32_16x16x32_bf16 v[118:121], v[138:141], v[178:181], v[118:121]
	v_mfma_f32_16x16x32_bf16 v[110:113], v[146:149], v[178:181], v[110:113]
	v_mfma_f32_16x16x32_bf16 v[102:105], v[138:141], v[190:193], v[102:105]
	v_mfma_f32_16x16x32_bf16 v[92:95], v[146:149], v[190:193], v[92:95]
	v_mfma_f32_16x16x32_bf16 v[84:87], v[138:141], v[202:205], v[84:87]
	v_mfma_f32_16x16x32_bf16 v[76:79], v[146:149], v[202:205], v[76:79]
	v_mfma_f32_16x16x32_bf16 v[126:129], v[142:145], v[174:177], v[126:129]
	v_mfma_f32_16x16x32_bf16 v[122:125], v[150:153], v[174:177], v[122:125]
	v_mfma_f32_16x16x32_bf16 v[118:121], v[142:145], v[182:185], v[118:121]
	v_mfma_f32_16x16x32_bf16 v[110:113], v[150:153], v[182:185], v[110:113]
	v_mfma_f32_16x16x32_bf16 v[102:105], v[142:145], v[194:197], v[102:105]
	v_mfma_f32_16x16x32_bf16 v[92:95], v[150:153], v[194:197], v[92:95]
	v_mfma_f32_16x16x32_bf16 v[84:87], v[142:145], v[206:209], v[84:87]
	v_mfma_f32_16x16x32_bf16 v[76:79], v[150:153], v[206:209], v[76:79]
	v_mfma_f32_16x16x32_bf16 v[114:117], v[154:157], v[170:173], v[114:117]
	v_mfma_f32_16x16x32_bf16 v[106:109], v[162:165], v[170:173], v[106:109]
	v_mfma_f32_16x16x32_bf16 v[98:101], v[154:157], v[178:181], v[98:101]
	v_mfma_f32_16x16x32_bf16 v[88:91], v[162:165], v[178:181], v[88:91]
	v_mfma_f32_16x16x32_bf16 v[80:83], v[154:157], v[190:193], v[80:83]
	v_mfma_f32_16x16x32_bf16 v[72:75], v[162:165], v[190:193], v[72:75]
	v_mfma_f32_16x16x32_bf16 v[68:71], v[154:157], v[202:205], v[68:71]
	v_mfma_f32_16x16x32_bf16 v[64:67], v[162:165], v[202:205], v[64:67]
	v_mfma_f32_16x16x32_bf16 v[114:117], v[158:161], v[174:177], v[114:117]
	v_mfma_f32_16x16x32_bf16 v[106:109], v[166:169], v[174:177], v[106:109]
	v_mfma_f32_16x16x32_bf16 v[98:101], v[158:161], v[182:185], v[98:101]
	v_mfma_f32_16x16x32_bf16 v[88:91], v[166:169], v[182:185], v[88:91]
	v_mfma_f32_16x16x32_bf16 v[80:83], v[158:161], v[194:197], v[80:83]
	v_mfma_f32_16x16x32_bf16 v[72:75], v[166:169], v[194:197], v[72:75]
	v_mfma_f32_16x16x32_bf16 v[68:71], v[158:161], v[206:209], v[68:71]
	v_mfma_f32_16x16x32_bf16 v[64:67], v[166:169], v[206:209], v[64:67]
	s_setprio 0
	s_barrier
	s_add_i32 s18, s35, s72
	s_mov_b32 m0, s18
	ds_read_b128 v[170:173], v200 offset:49152
	ds_read_b128 v[174:177], v200 offset:50176
	ds_read_b128 v[178:181], v200 offset:51200
	ds_read_b128 v[182:185], v200 offset:52224
	ds_read_b128 v[190:193], v200 offset:53248
	ds_read_b128 v[194:197], v200 offset:54272
	ds_read_b128 v[202:205], v200 offset:55296
	ds_read_b128 v[206:209], v200 offset:56320
	global_load_lds_dwordx4 v132, s[68:69]
	s_add_i32 m0, s18, 0x2000
	s_add_u32 s18, s68, 0x40000
	s_addc_u32 s19, s69, 0
	s_add_i32 s35, s44, s72
	global_load_lds_dwordx4 v136, s[68:69]
	s_mov_b32 m0, s35
	s_nop 0
	global_load_lds_dwordx4 v132, s[18:19]
	s_add_i32 m0, s35, 0x2000
	s_nop 0
	global_load_lds_dwordx4 v136, s[18:19]
	s_waitcnt vmcnt(6)
	s_waitcnt lgkmcnt(0)
	s_barrier
	s_setprio 1
	s_waitcnt lgkmcnt(0)
	v_mfma_f32_16x16x32_bf16 v[60:63], v[138:141], v[170:173], v[60:63]
	v_mfma_f32_16x16x32_bf16 v[56:59], v[146:149], v[170:173], v[56:59]
	v_mfma_f32_16x16x32_bf16 v[52:55], v[138:141], v[178:181], v[52:55]
	v_mfma_f32_16x16x32_bf16 v[44:47], v[146:149], v[178:181], v[44:47]
	v_mfma_f32_16x16x32_bf16 v[36:39], v[138:141], v[190:193], v[36:39]
	v_mfma_f32_16x16x32_bf16 v[28:31], v[146:149], v[190:193], v[28:31]
	v_mfma_f32_16x16x32_bf16 v[20:23], v[138:141], v[202:205], v[20:23]
	v_mfma_f32_16x16x32_bf16 v[12:15], v[146:149], v[202:205], v[12:15]
	v_mfma_f32_16x16x32_bf16 v[60:63], v[142:145], v[174:177], v[60:63]
	v_mfma_f32_16x16x32_bf16 v[56:59], v[150:153], v[174:177], v[56:59]
	v_mfma_f32_16x16x32_bf16 v[52:55], v[142:145], v[182:185], v[52:55]
	v_mfma_f32_16x16x32_bf16 v[44:47], v[150:153], v[182:185], v[44:47]
	v_mfma_f32_16x16x32_bf16 v[36:39], v[142:145], v[194:197], v[36:39]
	v_mfma_f32_16x16x32_bf16 v[28:31], v[150:153], v[194:197], v[28:31]
	v_mfma_f32_16x16x32_bf16 v[20:23], v[142:145], v[206:209], v[20:23]
	v_mfma_f32_16x16x32_bf16 v[12:15], v[150:153], v[206:209], v[12:15]
	v_mfma_f32_16x16x32_bf16 v[48:51], v[154:157], v[170:173], v[48:51]
	v_mfma_f32_16x16x32_bf16 v[40:43], v[162:165], v[170:173], v[40:43]
	v_mfma_f32_16x16x32_bf16 v[32:35], v[154:157], v[178:181], v[32:35]
	v_mfma_f32_16x16x32_bf16 v[24:27], v[162:165], v[178:181], v[24:27]
	v_mfma_f32_16x16x32_bf16 v[16:19], v[154:157], v[190:193], v[16:19]
	v_mfma_f32_16x16x32_bf16 v[8:11], v[162:165], v[190:193], v[8:11]
	v_mfma_f32_16x16x32_bf16 v[4:7], v[154:157], v[202:205], v[4:7]
	v_mfma_f32_16x16x32_bf16 v[0:3], v[162:165], v[202:205], v[0:3]
	v_mfma_f32_16x16x32_bf16 v[48:51], v[158:161], v[174:177], v[48:51]
	v_mfma_f32_16x16x32_bf16 v[40:43], v[166:169], v[174:177], v[40:43]
	v_mfma_f32_16x16x32_bf16 v[32:35], v[158:161], v[182:185], v[32:35]
	v_mfma_f32_16x16x32_bf16 v[24:27], v[166:169], v[182:185], v[24:27]
	v_mfma_f32_16x16x32_bf16 v[16:19], v[158:161], v[194:197], v[16:19]
	v_mfma_f32_16x16x32_bf16 v[8:11], v[166:169], v[194:197], v[8:11]
	v_mfma_f32_16x16x32_bf16 v[4:7], v[158:161], v[206:209], v[4:7]
	v_mfma_f32_16x16x32_bf16 v[0:3], v[166:169], v[206:209], v[0:3]
	s_add_i32 s92, s92, 2
	s_add_u32 vcc_hi, vcc_hi, 0x100
	s_addc_u32 s94, s94, 0
	s_setprio 0
	s_barrier
	s_cmp_gt_u32 s92, 13
	s_cbranch_scc0 .LBB0_433
	s_and_b64 vcc, exec, s[76:77]
	s_cbranch_vccz .LBB0_436
	s_barrier

.LBB0_703:
	s_add_i32 s35, 0, 0x10000
	v_add_u32_e32 v140, s35, v142
	s_add_i32 s49, 0, 0x14000
	ds_read_b128 v[136:139], v140
	ds_read_b128 v[144:147], v140 offset:1024
	ds_read_b128 v[148:151], v140 offset:2048
	ds_read_b128 v[152:155], v140 offset:3072
	v_add_u32_e32 v140, s49, v142
	ds_read_b128 v[156:159], v140
	ds_read_b128 v[160:163], v140 offset:1024
	ds_read_b128 v[164:167], v140 offset:2048
	ds_read_b128 v[168:171], v140 offset:3072
	ds_read_b128 v[172:175], v143
	ds_read_b128 v[176:179], v143 offset:1024
	ds_read_b128 v[180:183], v143 offset:2048
	ds_read_b128 v[190:193], v143 offset:3072
	ds_read_b128 v[194:197], v143 offset:4096
	ds_read_b128 v[198:201], v143 offset:5120
	ds_read_b128 v[202:205], v143 offset:6144
	ds_read_b128 v[206:209], v143 offset:7168
	s_cmp_eq_u32 s85, 40
	s_cselect_b32 s42, s8, s81
	s_cselect_b32 s43, s9, s82
	s_cselect_b32 s45, s59, s84
	s_cselect_b32 s44, s58, s83
	s_add_u32 s38, s42, 0x80
	s_addc_u32 s39, s43, 0
	s_add_u32 s62, s44, 0x80
	s_addc_u32 s63, s45, 0
	s_mov_b64 s[18:19], s[60:61]
	s_mov_b32 m0, s74
	s_nop 0
	global_load_lds_dwordx4 v130, s[18:19]
	s_mov_b32 m0, s75
	s_nop 0
	global_load_lds_dwordx4 v132, s[18:19]
	s_add_u32 s18, s18, 0xb0000
	s_addc_u32 s19, s19, 0
	s_add_i32 m0, s66, 0xc000
	s_nop 0
	global_load_lds_dwordx4 v130, s[18:19]
	s_add_i32 m0, s66, 0xe000
	s_nop 0
	global_load_lds_dwordx4 v132, s[18:19]
	s_waitcnt vmcnt(8)
	s_waitcnt lgkmcnt(0)
	s_barrier
	s_setprio 1
	s_waitcnt lgkmcnt(0)
	v_mfma_f32_16x16x32_bf16 v[126:129], v[136:139], v[172:175], v[126:129]
	v_mfma_f32_16x16x32_bf16 v[122:125], v[148:151], v[172:175], v[122:125]
	v_mfma_f32_16x16x32_bf16 v[110:113], v[136:139], v[180:183], v[110:113]
	v_mfma_f32_16x16x32_bf16 v[106:109], v[148:151], v[180:183], v[106:109]
	v_mfma_f32_16x16x32_bf16 v[92:95], v[136:139], v[194:197], v[92:95]
	v_mfma_f32_16x16x32_bf16 v[88:91], v[148:151], v[194:197], v[88:91]
	v_mfma_f32_16x16x32_bf16 v[76:79], v[136:139], v[202:205], v[76:79]
	v_mfma_f32_16x16x32_bf16 v[72:75], v[148:151], v[202:205], v[72:75]
	v_mfma_f32_16x16x32_bf16 v[126:129], v[144:147], v[176:179], v[126:129]
	v_mfma_f32_16x16x32_bf16 v[122:125], v[152:155], v[176:179], v[122:125]
	v_mfma_f32_16x16x32_bf16 v[110:113], v[144:147], v[190:193], v[110:113]
	v_mfma_f32_16x16x32_bf16 v[106:109], v[152:155], v[190:193], v[106:109]
	v_mfma_f32_16x16x32_bf16 v[92:95], v[144:147], v[198:201], v[92:95]
	v_mfma_f32_16x16x32_bf16 v[88:91], v[152:155], v[198:201], v[88:91]
	v_mfma_f32_16x16x32_bf16 v[76:79], v[144:147], v[206:209], v[76:79]
	v_mfma_f32_16x16x32_bf16 v[72:75], v[152:155], v[206:209], v[72:75]
	v_mfma_f32_16x16x32_bf16 v[118:121], v[156:159], v[172:175], v[118:121]
	v_mfma_f32_16x16x32_bf16 v[114:117], v[164:167], v[172:175], v[114:117]
	v_mfma_f32_16x16x32_bf16 v[102:105], v[156:159], v[180:183], v[102:105]
	v_mfma_f32_16x16x32_bf16 v[98:101], v[164:167], v[180:183], v[98:101]
	v_mfma_f32_16x16x32_bf16 v[84:87], v[156:159], v[194:197], v[84:87]
	v_mfma_f32_16x16x32_bf16 v[80:83], v[164:167], v[194:197], v[80:83]
	v_mfma_f32_16x16x32_bf16 v[68:71], v[156:159], v[202:205], v[68:71]
	v_mfma_f32_16x16x32_bf16 v[64:67], v[164:167], v[202:205], v[64:67]
	v_mfma_f32_16x16x32_bf16 v[118:121], v[160:163], v[176:179], v[118:121]
	v_mfma_f32_16x16x32_bf16 v[114:117], v[168:171], v[176:179], v[114:117]
	v_mfma_f32_16x16x32_bf16 v[102:105], v[160:163], v[190:193], v[102:105]
	v_mfma_f32_16x16x32_bf16 v[98:101], v[168:171], v[190:193], v[98:101]
	v_mfma_f32_16x16x32_bf16 v[84:87], v[160:163], v[198:201], v[84:87]
	v_mfma_f32_16x16x32_bf16 v[80:83], v[168:171], v[198:201], v[80:83]
	v_mfma_f32_16x16x32_bf16 v[68:71], v[160:163], v[206:209], v[68:71]
	v_mfma_f32_16x16x32_bf16 v[64:67], v[168:171], v[206:209], v[64:67]
	s_setprio 0
	s_barrier
	s_add_i32 s18, s35, s14
	s_mov_b32 m0, s18
	ds_read_b128 v[172:175], v143 offset:16384
	ds_read_b128 v[176:179], v143 offset:17408
	ds_read_b128 v[180:183], v143 offset:18432
	ds_read_b128 v[190:193], v143 offset:19456
	ds_read_b128 v[194:197], v143 offset:20480
	ds_read_b128 v[198:201], v143 offset:21504
	ds_read_b128 v[202:205], v143 offset:22528
	ds_read_b128 v[206:209], v143 offset:23552
	global_load_lds_dwordx4 v96, s[44:45]
	s_add_i32 m0, s18, 0x2000
	s_add_u32 s18, s44, 0xb0000
	s_addc_u32 s19, s45, 0
	s_add_i32 s35, s49, s14
	global_load_lds_dwordx4 v134, s[44:45]
	s_mov_b32 m0, s35
	s_nop 0
	global_load_lds_dwordx4 v96, s[18:19]
	s_add_i32 m0, s35, 0x2000
	s_nop 0
	global_load_lds_dwordx4 v134, s[18:19]
	s_waitcnt vmcnt(6)
	s_waitcnt lgkmcnt(0)
	s_barrier
	s_setprio 1
	s_waitcnt lgkmcnt(0)
	v_mfma_f32_16x16x32_bf16 v[60:63], v[136:139], v[172:175], v[60:63]
	v_mfma_f32_16x16x32_bf16 v[56:59], v[148:151], v[172:175], v[56:59]
	v_mfma_f32_16x16x32_bf16 v[44:47], v[136:139], v[180:183], v[44:47]
	v_mfma_f32_16x16x32_bf16 v[40:43], v[148:151], v[180:183], v[40:43]
	v_mfma_f32_16x16x32_bf16 v[28:31], v[136:139], v[194:197], v[28:31]
	v_mfma_f32_16x16x32_bf16 v[24:27], v[148:151], v[194:197], v[24:27]
	v_mfma_f32_16x16x32_bf16 v[12:15], v[136:139], v[202:205], v[12:15]
	v_mfma_f32_16x16x32_bf16 v[8:11], v[148:151], v[202:205], v[8:11]
	v_mfma_f32_16x16x32_bf16 v[60:63], v[144:147], v[176:179], v[60:63]
	v_mfma_f32_16x16x32_bf16 v[56:59], v[152:155], v[176:179], v[56:59]
	v_mfma_f32_16x16x32_bf16 v[44:47], v[144:147], v[190:193], v[44:47]
	v_mfma_f32_16x16x32_bf16 v[40:43], v[152:155], v[190:193], v[40:43]
	v_mfma_f32_16x16x32_bf16 v[28:31], v[144:147], v[198:201], v[28:31]
	v_mfma_f32_16x16x32_bf16 v[24:27], v[152:155], v[198:201], v[24:27]
	v_mfma_f32_16x16x32_bf16 v[12:15], v[144:147], v[206:209], v[12:15]
	v_mfma_f32_16x16x32_bf16 v[8:11], v[152:155], v[206:209], v[8:11]
	v_mfma_f32_16x16x32_bf16 v[52:55], v[156:159], v[172:175], v[52:55]
	v_mfma_f32_16x16x32_bf16 v[48:51], v[164:167], v[172:175], v[48:51]
	v_mfma_f32_16x16x32_bf16 v[36:39], v[156:159], v[180:183], v[36:39]
	v_mfma_f32_16x16x32_bf16 v[32:35], v[164:167], v[180:183], v[32:35]
	v_mfma_f32_16x16x32_bf16 v[20:23], v[156:159], v[194:197], v[20:23]
	v_mfma_f32_16x16x32_bf16 v[16:19], v[164:167], v[194:197], v[16:19]
	v_mfma_f32_16x16x32_bf16 v[4:7], v[156:159], v[202:205], v[4:7]
	v_mfma_f32_16x16x32_bf16 v[0:3], v[164:167], v[202:205], v[0:3]
	v_mfma_f32_16x16x32_bf16 v[52:55], v[160:163], v[176:179], v[52:55]
	v_mfma_f32_16x16x32_bf16 v[48:51], v[168:171], v[176:179], v[48:51]
	v_mfma_f32_16x16x32_bf16 v[36:39], v[160:163], v[190:193], v[36:39]
	v_mfma_f32_16x16x32_bf16 v[32:35], v[168:171], v[190:193], v[32:35]
	v_mfma_f32_16x16x32_bf16 v[20:23], v[160:163], v[198:201], v[20:23]
	v_mfma_f32_16x16x32_bf16 v[16:19], v[168:171], v[198:201], v[16:19]
	v_mfma_f32_16x16x32_bf16 v[4:7], v[160:163], v[206:209], v[4:7]
	v_mfma_f32_16x16x32_bf16 v[0:3], v[168:171], v[206:209], v[0:3]
	s_setprio 0
	s_barrier
	s_add_i32 s35, 0, 0x18000
	v_add_u32_e32 v140, s35, v142
	s_add_i32 s44, 0, 0x1c000
	ds_read_b128 v[136:139], v140
	ds_read_b128 v[144:147], v140 offset:1024
	ds_read_b128 v[148:151], v140 offset:2048
	ds_read_b128 v[152:155], v140 offset:3072
	v_add_u32_e32 v140, s44, v142
	ds_read_b128 v[156:159], v140
	ds_read_b128 v[160:163], v140 offset:1024
	ds_read_b128 v[164:167], v140 offset:2048
	ds_read_b128 v[168:171], v140 offset:3072
	s_mov_b32 m0, s66
	s_nop 0
	global_load_lds_dwordx4 v130, s[42:43]
	s_mov_b32 m0, s67
	s_nop 0
	global_load_lds_dwordx4 v132, s[42:43]
	s_add_u32 s18, s42, 0xb0000
	s_addc_u32 s19, s43, 0
	s_mov_b32 m0, s68
	ds_read_b128 v[172:175], v143 offset:32768
	ds_read_b128 v[176:179], v143 offset:33792
	ds_read_b128 v[180:183], v143 offset:34816
	ds_read_b128 v[190:193], v143 offset:35840
	ds_read_b128 v[194:197], v143 offset:36864
	ds_read_b128 v[198:201], v143 offset:37888
	ds_read_b128 v[202:205], v143 offset:38912
	ds_read_b128 v[206:209], v143 offset:39936
	global_load_lds_dwordx4 v130, s[18:19]
	s_mov_b32 m0, s69
	s_nop 0
	global_load_lds_dwordx4 v132, s[18:19]
	s_waitcnt vmcnt(8)
	s_waitcnt lgkmcnt(0)
	s_barrier
	s_setprio 1
	s_waitcnt lgkmcnt(0)
	v_mfma_f32_16x16x32_bf16 v[126:129], v[136:139], v[172:175], v[126:129]
	v_mfma_f32_16x16x32_bf16 v[122:125], v[148:151], v[172:175], v[122:125]
	v_mfma_f32_16x16x32_bf16 v[110:113], v[136:139], v[180:183], v[110:113]
	v_mfma_f32_16x16x32_bf16 v[106:109], v[148:151], v[180:183], v[106:109]
	v_mfma_f32_16x16x32_bf16 v[92:95], v[136:139], v[194:197], v[92:95]
	v_mfma_f32_16x16x32_bf16 v[88:91], v[148:151], v[194:197], v[88:91]
	v_mfma_f32_16x16x32_bf16 v[76:79], v[136:139], v[202:205], v[76:79]
	v_mfma_f32_16x16x32_bf16 v[72:75], v[148:151], v[202:205], v[72:75]
	v_mfma_f32_16x16x32_bf16 v[126:129], v[144:147], v[176:179], v[126:129]
	v_mfma_f32_16x16x32_bf16 v[122:125], v[152:155], v[176:179], v[122:125]
	v_mfma_f32_16x16x32_bf16 v[110:113], v[144:147], v[190:193], v[110:113]
	v_mfma_f32_16x16x32_bf16 v[106:109], v[152:155], v[190:193], v[106:109]
	v_mfma_f32_16x16x32_bf16 v[92:95], v[144:147], v[198:201], v[92:95]
	v_mfma_f32_16x16x32_bf16 v[88:91], v[152:155], v[198:201], v[88:91]
	v_mfma_f32_16x16x32_bf16 v[76:79], v[144:147], v[206:209], v[76:79]
	v_mfma_f32_16x16x32_bf16 v[72:75], v[152:155], v[206:209], v[72:75]
	v_mfma_f32_16x16x32_bf16 v[118:121], v[156:159], v[172:175], v[118:121]
	v_mfma_f32_16x16x32_bf16 v[114:117], v[164:167], v[172:175], v[114:117]
	v_mfma_f32_16x16x32_bf16 v[102:105], v[156:159], v[180:183], v[102:105]
	v_mfma_f32_16x16x32_bf16 v[98:101], v[164:167], v[180:183], v[98:101]
	v_mfma_f32_16x16x32_bf16 v[84:87], v[156:159], v[194:197], v[84:87]
	v_mfma_f32_16x16x32_bf16 v[80:83], v[164:167], v[194:197], v[80:83]
	v_mfma_f32_16x16x32_bf16 v[68:71], v[156:159], v[202:205], v[68:71]
	v_mfma_f32_16x16x32_bf16 v[64:67], v[164:167], v[202:205], v[64:67]
	v_mfma_f32_16x16x32_bf16 v[118:121], v[160:163], v[176:179], v[118:121]
	v_mfma_f32_16x16x32_bf16 v[114:117], v[168:171], v[176:179], v[114:117]
	v_mfma_f32_16x16x32_bf16 v[102:105], v[160:163], v[190:193], v[102:105]
	v_mfma_f32_16x16x32_bf16 v[98:101], v[168:171], v[190:193], v[98:101]
	v_mfma_f32_16x16x32_bf16 v[84:87], v[160:163], v[198:201], v[84:87]
	v_mfma_f32_16x16x32_bf16 v[80:83], v[168:171], v[198:201], v[80:83]
	v_mfma_f32_16x16x32_bf16 v[68:71], v[160:163], v[206:209], v[68:71]
	v_mfma_f32_16x16x32_bf16 v[64:67], v[168:171], v[206:209], v[64:67]
	s_setprio 0
	s_barrier
	s_add_i32 s18, s35, s14
	s_mov_b32 m0, s18
	ds_read_b128 v[172:175], v143 offset:49152
	ds_read_b128 v[176:179], v143 offset:50176
	ds_read_b128 v[180:183], v143 offset:51200
	ds_read_b128 v[190:193], v143 offset:52224
	ds_read_b128 v[194:197], v143 offset:53248
	ds_read_b128 v[198:201], v143 offset:54272
	ds_read_b128 v[202:205], v143 offset:55296
	ds_read_b128 v[206:209], v143 offset:56320
	global_load_lds_dwordx4 v96, s[62:63]
	s_add_i32 m0, s18, 0x2000
	s_add_u32 s18, s62, 0xb0000
	s_addc_u32 s19, s63, 0
	s_add_i32 s35, s44, s14
	global_load_lds_dwordx4 v134, s[62:63]
	s_mov_b32 m0, s35
	s_nop 0
	global_load_lds_dwordx4 v96, s[18:19]
	s_add_i32 m0, s35, 0x2000
	s_nop 0
	global_load_lds_dwordx4 v134, s[18:19]
	s_waitcnt vmcnt(6)
	s_waitcnt lgkmcnt(0)
	s_barrier
	s_setprio 1
	s_waitcnt lgkmcnt(0)
	v_mfma_f32_16x16x32_bf16 v[60:63], v[136:139], v[172:175], v[60:63]
	v_mfma_f32_16x16x32_bf16 v[56:59], v[148:151], v[172:175], v[56:59]
	v_mfma_f32_16x16x32_bf16 v[44:47], v[136:139], v[180:183], v[44:47]
	v_mfma_f32_16x16x32_bf16 v[40:43], v[148:151], v[180:183], v[40:43]
	v_mfma_f32_16x16x32_bf16 v[28:31], v[136:139], v[194:197], v[28:31]
	v_mfma_f32_16x16x32_bf16 v[24:27], v[148:151], v[194:197], v[24:27]
	v_mfma_f32_16x16x32_bf16 v[12:15], v[136:139], v[202:205], v[12:15]
	v_mfma_f32_16x16x32_bf16 v[8:11], v[148:151], v[202:205], v[8:11]
	v_mfma_f32_16x16x32_bf16 v[60:63], v[144:147], v[176:179], v[60:63]
	v_mfma_f32_16x16x32_bf16 v[56:59], v[152:155], v[176:179], v[56:59]
	v_mfma_f32_16x16x32_bf16 v[44:47], v[144:147], v[190:193], v[44:47]
	v_mfma_f32_16x16x32_bf16 v[40:43], v[152:155], v[190:193], v[40:43]
	v_mfma_f32_16x16x32_bf16 v[28:31], v[144:147], v[198:201], v[28:31]
	v_mfma_f32_16x16x32_bf16 v[24:27], v[152:155], v[198:201], v[24:27]
	v_mfma_f32_16x16x32_bf16 v[12:15], v[144:147], v[206:209], v[12:15]
	v_mfma_f32_16x16x32_bf16 v[8:11], v[152:155], v[206:209], v[8:11]
	v_mfma_f32_16x16x32_bf16 v[52:55], v[156:159], v[172:175], v[52:55]
	v_mfma_f32_16x16x32_bf16 v[48:51], v[164:167], v[172:175], v[48:51]
	v_mfma_f32_16x16x32_bf16 v[36:39], v[156:159], v[180:183], v[36:39]
	v_mfma_f32_16x16x32_bf16 v[32:35], v[164:167], v[180:183], v[32:35]
	v_mfma_f32_16x16x32_bf16 v[20:23], v[156:159], v[194:197], v[20:23]
	v_mfma_f32_16x16x32_bf16 v[16:19], v[164:167], v[194:197], v[16:19]
	v_mfma_f32_16x16x32_bf16 v[4:7], v[156:159], v[202:205], v[4:7]
	v_mfma_f32_16x16x32_bf16 v[0:3], v[164:167], v[202:205], v[0:3]
	v_mfma_f32_16x16x32_bf16 v[52:55], v[160:163], v[176:179], v[52:55]
	v_mfma_f32_16x16x32_bf16 v[48:51], v[168:171], v[176:179], v[48:51]
	v_mfma_f32_16x16x32_bf16 v[36:39], v[160:163], v[190:193], v[36:39]
	v_mfma_f32_16x16x32_bf16 v[32:35], v[168:171], v[190:193], v[32:35]
	v_mfma_f32_16x16x32_bf16 v[20:23], v[160:163], v[198:201], v[20:23]
	v_mfma_f32_16x16x32_bf16 v[16:19], v[168:171], v[198:201], v[16:19]
	v_mfma_f32_16x16x32_bf16 v[4:7], v[160:163], v[206:209], v[4:7]
	v_mfma_f32_16x16x32_bf16 v[0:3], v[168:171], v[206:209], v[0:3]
	s_add_i32 s85, s85, 2
	s_add_u32 s81, s81, 0x100
	s_addc_u32 s82, s82, 0
	s_add_u32 s83, s83, 0x100
	s_addc_u32 s84, s84, 0
	s_add_u32 s60, s60, 0x100
	s_addc_u32 s61, s61, 0
	s_setprio 0
	s_barrier
	s_cmp_gt_u32 s85, 41
	s_cbranch_scc0 .LBB0_703
	s_and_b64 vcc, exec, s[30:31]
	s_cbranch_vccz .LBB0_706
	s_barrier

.LBB0_740:
	s_add_i32 s35, 0, 0x10000
	s_add_i32 s49, 0, 0x14000
	v_add_u32_e32 v96, s35, v151
	v_add_u32_e32 v150, s49, v151
	ds_read_b128 v[138:141], v96
	ds_read_b128 v[142:145], v96 offset:1024
	ds_read_b128 v[146:149], v96 offset:2048
	ds_read_b128 v[156:159], v96 offset:3072
	ds_read_b128 v[160:163], v150
	ds_read_b128 v[164:167], v150 offset:1024
	ds_read_b128 v[168:171], v150 offset:2048
	ds_read_b128 v[172:175], v150 offset:3072
	ds_read_b128 v[176:179], v155
	ds_read_b128 v[180:183], v155 offset:1024
	ds_read_b128 v[190:193], v155 offset:2048
	ds_read_b128 v[194:197], v155 offset:3072
	ds_read_b128 v[198:201], v155 offset:4096
	ds_read_b128 v[202:205], v155 offset:5120
	ds_read_b128 v[206:209], v155 offset:6144
	ds_read_b128 v[210:213], v155 offset:7168
	s_add_u32 s18, s66, 0x80
	s_addc_u32 s19, s67, 0
	s_add_u32 s66, s66, 0x100
	s_addc_u32 s67, s67, 0
	s_cmp_eq_u32 s85, 12
	s_cselect_b32 s42, s81, s66
	s_cselect_b32 s43, s59, s67
	s_cselect_b32 s45, s31, s84
	s_cselect_b32 s44, s82, s83
	s_add_u32 s38, s42, 0x80
	s_addc_u32 s39, s43, 0
	s_add_u32 s68, s44, 0x80
	s_addc_u32 s69, s45, 0
	s_mov_b32 m0, s77
	s_nop 0
	global_load_lds_dwordx4 v136, s[18:19]
	s_mov_b32 m0, s78
	s_nop 0
	global_load_lds_dwordx4 v132, s[18:19]
	s_add_u32 s18, s18, 0x40000
	s_addc_u32 s19, s19, 0
	s_add_i32 m0, s65, 0xc000
	s_nop 0
	global_load_lds_dwordx4 v136, s[18:19]
	s_add_i32 m0, s65, 0xe000
	s_nop 0
	global_load_lds_dwordx4 v132, s[18:19]
	s_waitcnt vmcnt(8)
	s_waitcnt lgkmcnt(0)
	s_barrier
	s_setprio 1
	s_waitcnt lgkmcnt(0)
	v_mfma_f32_16x16x32_bf16 v[126:129], v[138:141], v[176:179], v[126:129]
	v_mfma_f32_16x16x32_bf16 v[118:121], v[146:149], v[176:179], v[118:121]
	v_mfma_f32_16x16x32_bf16 v[110:113], v[138:141], v[190:193], v[110:113]
	v_mfma_f32_16x16x32_bf16 v[102:105], v[146:149], v[190:193], v[102:105]
	v_mfma_f32_16x16x32_bf16 v[92:95], v[138:141], v[198:201], v[92:95]
	v_mfma_f32_16x16x32_bf16 v[84:87], v[146:149], v[198:201], v[84:87]
	v_mfma_f32_16x16x32_bf16 v[76:79], v[138:141], v[206:209], v[76:79]
	v_mfma_f32_16x16x32_bf16 v[68:71], v[146:149], v[206:209], v[68:71]
	v_mfma_f32_16x16x32_bf16 v[126:129], v[142:145], v[180:183], v[126:129]
	v_mfma_f32_16x16x32_bf16 v[118:121], v[156:159], v[180:183], v[118:121]
	v_mfma_f32_16x16x32_bf16 v[110:113], v[142:145], v[194:197], v[110:113]
	v_mfma_f32_16x16x32_bf16 v[102:105], v[156:159], v[194:197], v[102:105]
	v_mfma_f32_16x16x32_bf16 v[92:95], v[142:145], v[202:205], v[92:95]
	v_mfma_f32_16x16x32_bf16 v[84:87], v[156:159], v[202:205], v[84:87]
	v_mfma_f32_16x16x32_bf16 v[76:79], v[142:145], v[210:213], v[76:79]
	v_mfma_f32_16x16x32_bf16 v[68:71], v[156:159], v[210:213], v[68:71]
	v_mfma_f32_16x16x32_bf16 v[122:125], v[160:163], v[176:179], v[122:125]
	v_mfma_f32_16x16x32_bf16 v[114:117], v[168:171], v[176:179], v[114:117]
	v_mfma_f32_16x16x32_bf16 v[106:109], v[160:163], v[190:193], v[106:109]
	v_mfma_f32_16x16x32_bf16 v[98:101], v[168:171], v[190:193], v[98:101]
	v_mfma_f32_16x16x32_bf16 v[88:91], v[160:163], v[198:201], v[88:91]
	v_mfma_f32_16x16x32_bf16 v[80:83], v[168:171], v[198:201], v[80:83]
	v_mfma_f32_16x16x32_bf16 v[72:75], v[160:163], v[206:209], v[72:75]
	v_mfma_f32_16x16x32_bf16 v[64:67], v[168:171], v[206:209], v[64:67]
	v_mfma_f32_16x16x32_bf16 v[122:125], v[164:167], v[180:183], v[122:125]
	v_mfma_f32_16x16x32_bf16 v[114:117], v[172:175], v[180:183], v[114:117]
	v_mfma_f32_16x16x32_bf16 v[106:109], v[164:167], v[194:197], v[106:109]
	v_mfma_f32_16x16x32_bf16 v[98:101], v[172:175], v[194:197], v[98:101]
	v_mfma_f32_16x16x32_bf16 v[88:91], v[164:167], v[202:205], v[88:91]
	v_mfma_f32_16x16x32_bf16 v[80:83], v[172:175], v[202:205], v[80:83]
	v_mfma_f32_16x16x32_bf16 v[72:75], v[164:167], v[210:213], v[72:75]
	v_mfma_f32_16x16x32_bf16 v[64:67], v[172:175], v[210:213], v[64:67]
	s_setprio 0
	s_barrier
	s_add_i32 s18, s35, s47
	s_mov_b32 m0, s18
	ds_read_b128 v[176:179], v155 offset:16384
	ds_read_b128 v[180:183], v155 offset:17408
	ds_read_b128 v[190:193], v155 offset:18432
	ds_read_b128 v[194:197], v155 offset:19456
	ds_read_b128 v[198:201], v155 offset:20480
	ds_read_b128 v[202:205], v155 offset:21504
	ds_read_b128 v[206:209], v155 offset:22528
	ds_read_b128 v[210:213], v155 offset:23552
	global_load_lds_dwordx4 v134, s[44:45]
	s_add_i32 m0, s18, 0x2000
	s_add_u32 s18, s44, 0x40000
	s_addc_u32 s19, s45, 0
	s_add_i32 s35, s49, s47
	global_load_lds_dwordx4 v130, s[44:45]
	s_mov_b32 m0, s35
	s_nop 0
	global_load_lds_dwordx4 v134, s[18:19]
	s_add_i32 m0, s35, 0x2000
	s_nop 0
	global_load_lds_dwordx4 v130, s[18:19]
	s_waitcnt vmcnt(6)
	s_waitcnt lgkmcnt(0)
	s_barrier
	s_setprio 1
	s_waitcnt lgkmcnt(0)
	v_mfma_f32_16x16x32_bf16 v[60:63], v[138:141], v[176:179], v[60:63]
	v_mfma_f32_16x16x32_bf16 v[52:55], v[146:149], v[176:179], v[52:55]
	v_mfma_f32_16x16x32_bf16 v[44:47], v[138:141], v[190:193], v[44:47]
	v_mfma_f32_16x16x32_bf16 v[36:39], v[146:149], v[190:193], v[36:39]
	v_mfma_f32_16x16x32_bf16 v[28:31], v[138:141], v[198:201], v[28:31]
	v_mfma_f32_16x16x32_bf16 v[20:23], v[146:149], v[198:201], v[20:23]
	v_mfma_f32_16x16x32_bf16 v[12:15], v[138:141], v[206:209], v[12:15]
	v_mfma_f32_16x16x32_bf16 v[4:7], v[146:149], v[206:209], v[4:7]
	v_mfma_f32_16x16x32_bf16 v[60:63], v[142:145], v[180:183], v[60:63]
	v_mfma_f32_16x16x32_bf16 v[52:55], v[156:159], v[180:183], v[52:55]
	v_mfma_f32_16x16x32_bf16 v[44:47], v[142:145], v[194:197], v[44:47]
	v_mfma_f32_16x16x32_bf16 v[36:39], v[156:159], v[194:197], v[36:39]
	v_mfma_f32_16x16x32_bf16 v[28:31], v[142:145], v[202:205], v[28:31]
	v_mfma_f32_16x16x32_bf16 v[20:23], v[156:159], v[202:205], v[20:23]
	v_mfma_f32_16x16x32_bf16 v[12:15], v[142:145], v[210:213], v[12:15]
	v_mfma_f32_16x16x32_bf16 v[4:7], v[156:159], v[210:213], v[4:7]
	v_mfma_f32_16x16x32_bf16 v[56:59], v[160:163], v[176:179], v[56:59]
	v_mfma_f32_16x16x32_bf16 v[48:51], v[168:171], v[176:179], v[48:51]
	v_mfma_f32_16x16x32_bf16 v[40:43], v[160:163], v[190:193], v[40:43]
	v_mfma_f32_16x16x32_bf16 v[32:35], v[168:171], v[190:193], v[32:35]
	v_mfma_f32_16x16x32_bf16 v[24:27], v[160:163], v[198:201], v[24:27]
	v_mfma_f32_16x16x32_bf16 v[16:19], v[168:171], v[198:201], v[16:19]
	v_mfma_f32_16x16x32_bf16 v[8:11], v[160:163], v[206:209], v[8:11]
	v_mfma_f32_16x16x32_bf16 v[0:3], v[168:171], v[206:209], v[0:3]
	v_mfma_f32_16x16x32_bf16 v[56:59], v[164:167], v[180:183], v[56:59]
	v_mfma_f32_16x16x32_bf16 v[48:51], v[172:175], v[180:183], v[48:51]
	v_mfma_f32_16x16x32_bf16 v[40:43], v[164:167], v[194:197], v[40:43]
	v_mfma_f32_16x16x32_bf16 v[32:35], v[172:175], v[194:197], v[32:35]
	v_mfma_f32_16x16x32_bf16 v[24:27], v[164:167], v[202:205], v[24:27]
	v_mfma_f32_16x16x32_bf16 v[16:19], v[172:175], v[202:205], v[16:19]
	v_mfma_f32_16x16x32_bf16 v[8:11], v[164:167], v[210:213], v[8:11]
	v_mfma_f32_16x16x32_bf16 v[0:3], v[172:175], v[210:213], v[0:3]
	s_setprio 0
	s_barrier
	s_add_i32 s35, 0, 0x18000
	v_add_u32_e32 v96, s35, v151
	s_add_i32 s44, 0, 0x1c000
	ds_read_b128 v[138:141], v96
	ds_read_b128 v[142:145], v96 offset:1024
	ds_read_b128 v[146:149], v96 offset:2048
	ds_read_b128 v[156:159], v96 offset:3072
	v_add_u32_e32 v96, s44, v151
	ds_read_b128 v[160:163], v96
	ds_read_b128 v[164:167], v96 offset:1024
	ds_read_b128 v[168:171], v96 offset:2048
	ds_read_b128 v[172:175], v96 offset:3072
	s_mov_b32 m0, s65
	s_nop 0
	global_load_lds_dwordx4 v136, s[42:43]
	s_mov_b32 m0, s72
	s_nop 0
	global_load_lds_dwordx4 v132, s[42:43]
	s_add_u32 s18, s42, 0x40000
	s_addc_u32 s19, s43, 0
	s_mov_b32 m0, s73
	ds_read_b128 v[176:179], v155 offset:32768
	ds_read_b128 v[180:183], v155 offset:33792
	ds_read_b128 v[190:193], v155 offset:34816
	ds_read_b128 v[194:197], v155 offset:35840
	ds_read_b128 v[198:201], v155 offset:36864
	ds_read_b128 v[202:205], v155 offset:37888
	ds_read_b128 v[206:209], v155 offset:38912
	ds_read_b128 v[210:213], v155 offset:39936
	global_load_lds_dwordx4 v136, s[18:19]
	s_mov_b32 m0, s74
	s_nop 0
	global_load_lds_dwordx4 v132, s[18:19]
	s_waitcnt vmcnt(8)
	s_waitcnt lgkmcnt(0)
	s_barrier
	s_setprio 1
	s_waitcnt lgkmcnt(0)
	v_mfma_f32_16x16x32_bf16 v[126:129], v[138:141], v[176:179], v[126:129]
	v_mfma_f32_16x16x32_bf16 v[118:121], v[146:149], v[176:179], v[118:121]
	v_mfma_f32_16x16x32_bf16 v[110:113], v[138:141], v[190:193], v[110:113]
	v_mfma_f32_16x16x32_bf16 v[102:105], v[146:149], v[190:193], v[102:105]
	v_mfma_f32_16x16x32_bf16 v[92:95], v[138:141], v[198:201], v[92:95]
	v_mfma_f32_16x16x32_bf16 v[84:87], v[146:149], v[198:201], v[84:87]
	v_mfma_f32_16x16x32_bf16 v[76:79], v[138:141], v[206:209], v[76:79]
	v_mfma_f32_16x16x32_bf16 v[68:71], v[146:149], v[206:209], v[68:71]
	v_mfma_f32_16x16x32_bf16 v[126:129], v[142:145], v[180:183], v[126:129]
	v_mfma_f32_16x16x32_bf16 v[118:121], v[156:159], v[180:183], v[118:121]
	v_mfma_f32_16x16x32_bf16 v[110:113], v[142:145], v[194:197], v[110:113]
	v_mfma_f32_16x16x32_bf16 v[102:105], v[156:159], v[194:197], v[102:105]
	v_mfma_f32_16x16x32_bf16 v[92:95], v[142:145], v[202:205], v[92:95]
	v_mfma_f32_16x16x32_bf16 v[84:87], v[156:159], v[202:205], v[84:87]
	v_mfma_f32_16x16x32_bf16 v[76:79], v[142:145], v[210:213], v[76:79]
	v_mfma_f32_16x16x32_bf16 v[68:71], v[156:159], v[210:213], v[68:71]
	v_mfma_f32_16x16x32_bf16 v[122:125], v[160:163], v[176:179], v[122:125]
	v_mfma_f32_16x16x32_bf16 v[114:117], v[168:171], v[176:179], v[114:117]
	v_mfma_f32_16x16x32_bf16 v[106:109], v[160:163], v[190:193], v[106:109]
	v_mfma_f32_16x16x32_bf16 v[98:101], v[168:171], v[190:193], v[98:101]
	v_mfma_f32_16x16x32_bf16 v[88:91], v[160:163], v[198:201], v[88:91]
	v_mfma_f32_16x16x32_bf16 v[80:83], v[168:171], v[198:201], v[80:83]
	v_mfma_f32_16x16x32_bf16 v[72:75], v[160:163], v[206:209], v[72:75]
	v_mfma_f32_16x16x32_bf16 v[64:67], v[168:171], v[206:209], v[64:67]
	v_mfma_f32_16x16x32_bf16 v[122:125], v[164:167], v[180:183], v[122:125]
	v_mfma_f32_16x16x32_bf16 v[114:117], v[172:175], v[180:183], v[114:117]
	v_mfma_f32_16x16x32_bf16 v[106:109], v[164:167], v[194:197], v[106:109]
	v_mfma_f32_16x16x32_bf16 v[98:101], v[172:175], v[194:197], v[98:101]
	v_mfma_f32_16x16x32_bf16 v[88:91], v[164:167], v[202:205], v[88:91]
	v_mfma_f32_16x16x32_bf16 v[80:83], v[172:175], v[202:205], v[80:83]
	v_mfma_f32_16x16x32_bf16 v[72:75], v[164:167], v[210:213], v[72:75]
	v_mfma_f32_16x16x32_bf16 v[64:67], v[172:175], v[210:213], v[64:67]
	s_setprio 0
	s_barrier
	s_add_i32 s18, s35, s47
	s_mov_b32 m0, s18
	ds_read_b128 v[176:179], v155 offset:49152
	ds_read_b128 v[180:183], v155 offset:50176
	ds_read_b128 v[190:193], v155 offset:51200
	ds_read_b128 v[194:197], v155 offset:52224
	ds_read_b128 v[198:201], v155 offset:53248
	ds_read_b128 v[202:205], v155 offset:54272
	ds_read_b128 v[206:209], v155 offset:55296
	ds_read_b128 v[210:213], v155 offset:56320
	global_load_lds_dwordx4 v134, s[68:69]
	s_add_i32 m0, s18, 0x2000
	s_add_u32 s18, s68, 0x40000
	s_addc_u32 s19, s69, 0
	s_add_i32 s35, s44, s47
	global_load_lds_dwordx4 v130, s[68:69]
	s_mov_b32 m0, s35
	s_nop 0
	global_load_lds_dwordx4 v134, s[18:19]
	s_add_i32 m0, s35, 0x2000
	s_nop 0
	global_load_lds_dwordx4 v130, s[18:19]
	s_waitcnt vmcnt(6)
	s_cmp_lg_u32 s85, 12
	s_cbranch_scc1 .Lswi_ssq_skip
	global_load_dwordx4 v[220:223], v[252:253], off
	global_load_dwordx4 v[224:227], v[252:253], off offset:1024
	global_load_dwordx4 v[228:231], v[252:253], off offset:2048
	global_load_dwordx4 v[232:235], v[252:253], off offset:3072
	global_load_dwordx4 v[236:239], v[184:185], off
	global_load_dwordx4 v[240:243], v[184:185], off offset:1024
	global_load_dwordx4 v[244:247], v[184:185], off offset:2048
	global_load_dwordx4 v[248:251], v[184:185], off offset:3072
.Lswi_ssq_skip:
	s_waitcnt lgkmcnt(0)
	s_barrier
	s_setprio 1
	s_waitcnt lgkmcnt(0)
	v_mfma_f32_16x16x32_bf16 v[60:63], v[138:141], v[176:179], v[60:63]
	v_mfma_f32_16x16x32_bf16 v[52:55], v[146:149], v[176:179], v[52:55]
	v_mfma_f32_16x16x32_bf16 v[44:47], v[138:141], v[190:193], v[44:47]
	v_mfma_f32_16x16x32_bf16 v[36:39], v[146:149], v[190:193], v[36:39]
	v_mfma_f32_16x16x32_bf16 v[28:31], v[138:141], v[198:201], v[28:31]
	v_mfma_f32_16x16x32_bf16 v[20:23], v[146:149], v[198:201], v[20:23]
	v_mfma_f32_16x16x32_bf16 v[12:15], v[138:141], v[206:209], v[12:15]
	v_mfma_f32_16x16x32_bf16 v[4:7], v[146:149], v[206:209], v[4:7]
	v_mfma_f32_16x16x32_bf16 v[60:63], v[142:145], v[180:183], v[60:63]
	v_mfma_f32_16x16x32_bf16 v[52:55], v[156:159], v[180:183], v[52:55]
	v_mfma_f32_16x16x32_bf16 v[44:47], v[142:145], v[194:197], v[44:47]
	v_mfma_f32_16x16x32_bf16 v[36:39], v[156:159], v[194:197], v[36:39]
	v_mfma_f32_16x16x32_bf16 v[28:31], v[142:145], v[202:205], v[28:31]
	v_mfma_f32_16x16x32_bf16 v[20:23], v[156:159], v[202:205], v[20:23]
	v_mfma_f32_16x16x32_bf16 v[12:15], v[142:145], v[210:213], v[12:15]
	v_mfma_f32_16x16x32_bf16 v[4:7], v[156:159], v[210:213], v[4:7]
	v_mfma_f32_16x16x32_bf16 v[56:59], v[160:163], v[176:179], v[56:59]
	v_mfma_f32_16x16x32_bf16 v[48:51], v[168:171], v[176:179], v[48:51]
	v_mfma_f32_16x16x32_bf16 v[40:43], v[160:163], v[190:193], v[40:43]
	v_mfma_f32_16x16x32_bf16 v[32:35], v[168:171], v[190:193], v[32:35]
	v_mfma_f32_16x16x32_bf16 v[24:27], v[160:163], v[198:201], v[24:27]
	v_mfma_f32_16x16x32_bf16 v[16:19], v[168:171], v[198:201], v[16:19]
	v_mfma_f32_16x16x32_bf16 v[8:11], v[160:163], v[206:209], v[8:11]
	v_mfma_f32_16x16x32_bf16 v[0:3], v[168:171], v[206:209], v[0:3]
	v_mfma_f32_16x16x32_bf16 v[56:59], v[164:167], v[180:183], v[56:59]
	v_mfma_f32_16x16x32_bf16 v[48:51], v[172:175], v[180:183], v[48:51]
	v_mfma_f32_16x16x32_bf16 v[40:43], v[164:167], v[194:197], v[40:43]
	v_mfma_f32_16x16x32_bf16 v[32:35], v[172:175], v[194:197], v[32:35]
	v_mfma_f32_16x16x32_bf16 v[24:27], v[164:167], v[202:205], v[24:27]
	v_mfma_f32_16x16x32_bf16 v[16:19], v[172:175], v[202:205], v[16:19]
	v_mfma_f32_16x16x32_bf16 v[8:11], v[164:167], v[210:213], v[8:11]
	v_mfma_f32_16x16x32_bf16 v[0:3], v[172:175], v[210:213], v[0:3]
	s_add_i32 s85, s85, 2
	s_add_u32 s83, s83, 0x100
	s_addc_u32 s84, s84, 0
	s_setprio 0
	s_barrier
	s_cmp_gt_u32 s85, 13
	s_cbranch_scc0 .LBB0_740
	s_and_b64 vcc, exec, s[28:29]
	s_cbranch_vccz .LBB0_743
	s_barrier
